# v078 + nt on the one-time row loads (h1, d1) of the output norm phase
# speedup vs baseline: 1.0015x; 1.0015x over previous
.LBB0_836:
	v_add_co_u32_e64 v52, s[0:1], s6, v32
	v_add_co_u32_e32 v48, vcc, 0xf7fff000, v32
	s_nop 0
	v_addc_co_u32_e64 v53, s[0:1], -1, v33, s[0:1]
	global_load_dwordx2 v[34:35], v[32:33], off offset:-4096 nt
	global_load_dwordx2 v[36:37], v[32:33], off offset:-3584 nt
	global_load_dwordx2 v[38:39], v[32:33], off offset:-3072 nt
	global_load_dwordx2 v[40:41], v[32:33], off offset:-2560 nt
	global_load_dwordx2 v[42:43], v[32:33], off offset:-2048 nt
	global_load_dwordx2 v[44:45], v[32:33], off offset:-1536 nt
	global_load_dwordx2 v[50:51], v[32:33], off offset:-1024 nt
	global_load_dwordx2 v[54:55], v[32:33], off offset:-512 nt
	global_load_dwordx2 v[56:57], v[32:33], off nt
	global_load_dwordx4 v[0:3], v[4:5], off
	global_load_dwordx2 v[58:59], v[52:53], off offset:-3072 nt
	global_load_dwordx2 v[60:61], v[52:53], off offset:-2560 nt
	global_load_dwordx2 v[62:63], v[52:53], off offset:-2048 nt
	global_load_dwordx2 v[68:69], v[52:53], off offset:-1536 nt
	global_load_dwordx2 v[70:71], v[52:53], off offset:-1024 nt
	global_load_dwordx2 v[72:73], v[52:53], off offset:-512 nt
	v_addc_co_u32_e32 v49, vcc, -1, v33, vcc
	global_load_dwordx2 v[76:77], v[52:53], off nt
	v_add_co_u32_e32 v74, vcc, 0xfffff000, v32
	v_mov_b32_e32 v67, 0
	s_nop 0
	v_addc_co_u32_e32 v75, vcc, -1, v33, vcc
	global_load_dwordx2 v[78:79], v[48:49], off offset:-3584 nt
	global_load_dwordx2 v[80:81], v[48:49], off offset:-3072 nt
	global_load_dwordx2 v[82:83], v[48:49], off offset:-2560 nt
	global_load_dwordx2 v[84:85], v[48:49], off offset:-2048 nt
	global_load_dwordx2 v[86:87], v[48:49], off offset:-1536 nt
	global_load_dwordx2 v[88:89], v[48:49], off offset:-1024 nt
	global_load_dwordx2 v[90:91], v[48:49], off offset:-512 nt
	global_load_dwordx2 v[92:93], v[48:49], off nt
	global_load_dwordx2 v[94:95], v[74:75], off offset:-3584 nt
	global_load_dwordx2 v[96:97], v[74:75], off offset:-3072 nt
	global_load_dwordx2 v[98:99], v[74:75], off offset:-2560 nt
	global_load_dwordx2 v[100:101], v[74:75], off offset:-2048 nt
	global_load_dwordx2 v[102:103], v[74:75], off offset:-1536 nt
	global_load_dwordx2 v[104:105], v[74:75], off offset:-1024 nt
	global_load_dwordx2 v[106:107], v[74:75], off offset:-512 nt
	s_nop 0
	global_load_dwordx2 v[74:75], v[52:53], off offset:-3584 nt
	v_mov_b32_e32 v158, 0
	v_add_co_u32_e64 v46, s[0:1], s8, v30
	s_add_i32 s2, s2, s96
	s_nop 0
	v_addc_co_u32_e64 v47, s[0:1], -1, v31, s[0:1]
	s_cmpk_lt_i32 s2, 0x4000
	v_lshl_add_u64 v[32:33], v[32:33], 0, s[10:11]
	s_waitcnt vmcnt(32)
	v_lshlrev_b32_e32 v108, 16, v34
	v_and_b32_e32 v109, 0xffff0000, v34
	v_lshlrev_b32_e32 v110, 16, v35
	v_and_b32_e32 v111, 0xffff0000, v35
	s_waitcnt vmcnt(31)
	v_lshlrev_b32_e32 v112, 16, v36
	v_and_b32_e32 v113, 0xffff0000, v36
	v_lshlrev_b32_e32 v114, 16, v37
	v_and_b32_e32 v115, 0xffff0000, v37
	s_waitcnt vmcnt(30)
	v_lshlrev_b32_e32 v34, 16, v38
	v_and_b32_e32 v35, 0xffff0000, v38
	v_lshlrev_b32_e32 v36, 16, v39
	v_and_b32_e32 v37, 0xffff0000, v39
	s_waitcnt vmcnt(29)
	v_lshlrev_b32_e32 v38, 16, v40
	v_and_b32_e32 v39, 0xffff0000, v40
	s_waitcnt vmcnt(28)
	v_lshlrev_b32_e32 v48, 16, v42
	v_and_b32_e32 v49, 0xffff0000, v42
	v_lshlrev_b32_e32 v42, 16, v43
	v_and_b32_e32 v43, 0xffff0000, v43
	s_waitcnt vmcnt(27)
	v_lshlrev_b32_e32 v116, 16, v44
	v_and_b32_e32 v117, 0xffff0000, v44
	v_lshlrev_b32_e32 v44, 16, v45
	v_and_b32_e32 v45, 0xffff0000, v45
	s_waitcnt vmcnt(26)
	v_lshlrev_b32_e32 v118, 16, v50
	v_and_b32_e32 v119, 0xffff0000, v50
	v_lshlrev_b32_e32 v120, 16, v51
	v_and_b32_e32 v121, 0xffff0000, v51
	s_waitcnt vmcnt(25)
	v_lshlrev_b32_e32 v122, 16, v54
	v_and_b32_e32 v123, 0xffff0000, v54
	v_lshlrev_b32_e32 v124, 16, v55
	v_and_b32_e32 v125, 0xffff0000, v55
	s_waitcnt vmcnt(24)
	v_lshlrev_b32_e32 v128, 16, v57
	v_and_b32_e32 v129, 0xffff0000, v57
	s_waitcnt vmcnt(22)
	v_lshlrev_b32_e32 v50, 16, v58
	v_and_b32_e32 v51, 0xffff0000, v58
	v_lshlrev_b32_e32 v52, 16, v59
	v_and_b32_e32 v53, 0xffff0000, v59
	s_waitcnt vmcnt(21)
	v_lshlrev_b32_e32 v54, 16, v60
	v_and_b32_e32 v55, 0xffff0000, v60
	s_waitcnt vmcnt(20)
	v_lshlrev_b32_e32 v130, 16, v62
	v_and_b32_e32 v131, 0xffff0000, v62
	v_lshlrev_b32_e32 v132, 16, v63
	v_and_b32_e32 v133, 0xffff0000, v63
	s_waitcnt vmcnt(19)
	v_lshlrev_b32_e32 v134, 16, v68
	v_and_b32_e32 v135, 0xffff0000, v68
	v_lshlrev_b32_e32 v68, 16, v69
	v_and_b32_e32 v69, 0xffff0000, v69
	s_waitcnt vmcnt(18)
	v_lshlrev_b32_e32 v136, 16, v70
	v_and_b32_e32 v137, 0xffff0000, v70
	v_lshlrev_b32_e32 v70, 16, v71
	v_and_b32_e32 v71, 0xffff0000, v71
	s_waitcnt vmcnt(17)
	v_lshlrev_b32_e32 v138, 16, v72
	v_and_b32_e32 v139, 0xffff0000, v72
	v_lshlrev_b32_e32 v72, 16, v73
	v_and_b32_e32 v73, 0xffff0000, v73
	s_waitcnt vmcnt(16)
	v_lshlrev_b32_e32 v140, 16, v76
	v_and_b32_e32 v141, 0xffff0000, v76
	v_lshlrev_b32_e32 v76, 16, v77
	v_and_b32_e32 v77, 0xffff0000, v77
	v_lshlrev_b32_e32 v126, 16, v56
	v_and_b32_e32 v127, 0xffff0000, v56
	v_lshlrev_b32_e32 v56, 16, v61
	v_and_b32_e32 v57, 0xffff0000, v61
	s_waitcnt vmcnt(15)
	v_lshlrev_b32_e32 v142, 16, v78
	v_and_b32_e32 v143, 0xffff0000, v78
	v_lshlrev_b32_e32 v78, 16, v79
	v_and_b32_e32 v79, 0xffff0000, v79
	s_waitcnt vmcnt(14)
	v_lshlrev_b32_e32 v144, 16, v80
	v_and_b32_e32 v145, 0xffff0000, v80
	v_lshlrev_b32_e32 v80, 16, v81
	v_and_b32_e32 v81, 0xffff0000, v81
	s_waitcnt vmcnt(8)
	v_lshlrev_b32_e32 v156, 16, v92
	v_and_b32_e32 v157, 0xffff0000, v92
	v_lshlrev_b32_e32 v92, 16, v93
	v_and_b32_e32 v93, 0xffff0000, v93
	v_pk_add_f32 v[60:61], v[52:53], v[36:37]
	v_pk_add_f32 v[62:63], v[50:51], v[34:35]
	v_pk_add_f32 v[58:59], v[54:55], v[38:39]
	v_pk_add_f32 v[52:53], v[132:133], v[42:43]
	v_pk_add_f32 v[54:55], v[130:131], v[48:49]
	v_pk_add_f32 v[48:49], v[68:69], v[44:45]
	v_pk_add_f32 v[42:43], v[70:71], v[120:121]
	v_pk_add_f32 v[38:39], v[72:73], v[124:125]
	v_pk_add_f32 v[34:35], v[76:77], v[128:129]
	s_waitcnt vmcnt(7)
	v_lshlrev_b32_e32 v68, 16, v94
	v_and_b32_e32 v69, 0xffff0000, v94
	v_lshlrev_b32_e32 v70, 16, v95
	v_and_b32_e32 v71, 0xffff0000, v95
	s_waitcnt vmcnt(6)
	v_lshlrev_b32_e32 v72, 16, v96
	v_and_b32_e32 v73, 0xffff0000, v96
	v_lshlrev_b32_e32 v76, 16, v97
	v_and_b32_e32 v77, 0xffff0000, v97
	v_lshlrev_b32_e32 v146, 16, v82
	v_and_b32_e32 v147, 0xffff0000, v82
	v_lshlrev_b32_e32 v82, 16, v83
	v_and_b32_e32 v83, 0xffff0000, v83
	v_lshlrev_b32_e32 v150, 16, v86
	v_and_b32_e32 v151, 0xffff0000, v86
	v_lshlrev_b32_e32 v86, 16, v87
	v_and_b32_e32 v87, 0xffff0000, v87
	v_lshlrev_b32_e32 v152, 16, v88
	v_and_b32_e32 v153, 0xffff0000, v88
	v_lshlrev_b32_e32 v88, 16, v89
	v_and_b32_e32 v89, 0xffff0000, v89
	v_lshlrev_b32_e32 v154, 16, v90
	v_and_b32_e32 v155, 0xffff0000, v90
	v_lshlrev_b32_e32 v90, 16, v91
	v_and_b32_e32 v91, 0xffff0000, v91
	v_pk_add_f32 v[50:51], v[134:135], v[116:117]
	v_pk_add_f32 v[44:45], v[136:137], v[118:119]
	s_waitcnt vmcnt(5)
	v_lshlrev_b32_e32 v94, 16, v98
	v_and_b32_e32 v95, 0xffff0000, v98
	v_lshlrev_b32_e32 v96, 16, v99
	v_and_b32_e32 v97, 0xffff0000, v99
	s_waitcnt vmcnt(3)
	v_lshlrev_b32_e32 v116, 16, v102
	v_and_b32_e32 v117, 0xffff0000, v102
	v_lshlrev_b32_e32 v102, 16, v103
	v_and_b32_e32 v103, 0xffff0000, v103
	s_waitcnt vmcnt(2)
	v_lshlrev_b32_e32 v118, 16, v104
	v_and_b32_e32 v119, 0xffff0000, v104
	v_lshlrev_b32_e32 v104, 16, v105
	v_and_b32_e32 v105, 0xffff0000, v105
	s_waitcnt vmcnt(1)
	v_lshlrev_b32_e32 v120, 16, v106
	v_and_b32_e32 v121, 0xffff0000, v106
	v_lshlrev_b32_e32 v106, 16, v107
	v_and_b32_e32 v107, 0xffff0000, v107
	v_pk_add_f32 v[92:93], v[92:93], v[110:111]
	v_pk_add_f32 v[108:109], v[156:157], v[108:109]
	v_pk_add_f32 v[70:71], v[78:79], v[70:71]
	v_pk_add_f32 v[68:69], v[142:143], v[68:69]
	v_pk_add_f32 v[76:77], v[80:81], v[76:77]
	v_pk_add_f32 v[72:73], v[144:145], v[72:73]
	v_lshlrev_b32_e32 v148, 16, v84
	v_and_b32_e32 v149, 0xffff0000, v84
	v_lshlrev_b32_e32 v84, 16, v85
	v_and_b32_e32 v85, 0xffff0000, v85
	v_lshlrev_b32_e32 v98, 16, v100
	v_and_b32_e32 v99, 0xffff0000, v100
	v_lshlrev_b32_e32 v100, 16, v101
	v_and_b32_e32 v101, 0xffff0000, v101
	s_waitcnt vmcnt(0)
	v_lshlrev_b32_e32 v110, 16, v74
	v_and_b32_e32 v111, 0xffff0000, v74
	v_pk_add_f32 v[78:79], v[82:83], v[96:97]
	v_pk_add_f32 v[80:81], v[146:147], v[94:95]
	v_pk_add_f32 v[86:87], v[86:87], v[102:103]
	v_pk_add_f32 v[88:89], v[88:89], v[104:105]
	v_pk_add_f32 v[90:91], v[90:91], v[106:107]
	v_mul_f32_e32 v102, v109, v109
	v_mul_f32_e32 v103, v93, v93
	v_mul_f32_e32 v104, v69, v69
	v_mul_f32_e32 v105, v71, v71
	v_mul_f32_e32 v106, v73, v73
	v_mul_f32_e32 v107, v77, v77
	v_pk_add_f32 v[82:83], v[84:85], v[100:101]
	v_pk_add_f32 v[84:85], v[148:149], v[98:99]
	v_pk_add_f32 v[100:101], v[110:111], v[112:113]
	v_mul_f32_e32 v110, v81, v81
	v_mul_f32_e32 v111, v79, v79
	v_fmac_f32_e32 v102, v108, v108
	v_fmac_f32_e32 v103, v92, v92
	v_fmac_f32_e32 v104, v68, v68
	v_fmac_f32_e32 v105, v70, v70
	v_fmac_f32_e32 v106, v72, v72
	v_fmac_f32_e32 v107, v76, v76
	v_lshlrev_b32_e32 v74, 16, v75
	v_and_b32_e32 v75, 0xffff0000, v75
	v_pk_add_f32 v[94:95], v[150:151], v[116:117]
	v_mul_f32_e32 v112, v85, v85
	v_mul_f32_e32 v113, v83, v83
	v_fmac_f32_e32 v110, v80, v80
	v_fmac_f32_e32 v111, v78, v78
	v_add_f32_e32 v102, v102, v103
	v_add_f32_e32 v103, v104, v105
	v_add_f32_e32 v104, v106, v107
	v_pk_add_f32 v[96:97], v[152:153], v[118:119]
	v_pk_add_f32 v[74:75], v[74:75], v[114:115]
	v_mul_f32_e32 v114, v95, v95
	v_mul_f32_e32 v115, v87, v87
	v_fmac_f32_e32 v112, v84, v84
	v_fmac_f32_e32 v113, v82, v82
	v_add_f32_e32 v105, v110, v111
	v_add_f32_e32 v103, v103, v104
	v_pk_add_f32 v[98:99], v[154:155], v[120:121]
	v_mul_f32_e32 v116, v97, v97
	v_mul_f32_e32 v117, v89, v89
	v_fmac_f32_e32 v114, v94, v94
	v_fmac_f32_e32 v115, v86, v86
	v_add_f32_e32 v106, v112, v113
	v_add_f32_e32 v103, v103, v105
	v_mul_f32_e32 v118, v99, v99
	v_mul_f32_e32 v119, v91, v91
	v_fmac_f32_e32 v116, v96, v96
	v_fmac_f32_e32 v117, v88, v88
	v_add_f32_e32 v107, v114, v115
	v_add_f32_e32 v103, v103, v106
	v_fmac_f32_e32 v118, v98, v98
	v_fmac_f32_e32 v119, v90, v90
	v_add_f32_e32 v110, v116, v117
	v_add_f32_e32 v103, v103, v107
	v_lshlrev_b32_e32 v40, 16, v41
	v_and_b32_e32 v41, 0xffff0000, v41
	v_mul_f32_e32 v120, v101, v101
	v_mul_f32_e32 v121, v75, v75
	v_add_f32_e32 v111, v118, v119
	v_add_f32_e32 v103, v103, v110
	v_pk_add_f32 v[56:57], v[56:57], v[40:41]
	v_pk_add_f32 v[40:41], v[138:139], v[122:123]
	v_mul_f32_e32 v122, v63, v63
	v_mul_f32_e32 v123, v61, v61
	v_fmac_f32_e32 v120, v100, v100
	v_fmac_f32_e32 v121, v74, v74
	v_add_f32_e32 v103, v103, v111
	v_mul_f32_e32 v124, v59, v59
	v_mul_f32_e32 v125, v57, v57
	v_fmac_f32_e32 v122, v62, v62
	v_fmac_f32_e32 v123, v60, v60
	v_add_f32_e32 v112, v120, v121
	v_add_f32_e32 v102, v103, v102
	v_pk_add_f32 v[36:37], v[140:141], v[126:127]
	v_mul_f32_e32 v126, v55, v55
	v_mul_f32_e32 v127, v53, v53
	v_fmac_f32_e32 v124, v58, v58
	v_fmac_f32_e32 v125, v56, v56
	v_add_f32_e32 v122, v122, v123
	v_add_f32_e32 v102, v102, v112
	v_mul_f32_e32 v128, v51, v51
	v_mul_f32_e32 v129, v49, v49
	v_fmac_f32_e32 v126, v54, v54
	v_fmac_f32_e32 v127, v52, v52
	v_add_f32_e32 v123, v124, v125
	v_add_f32_e32 v102, v102, v122
	v_mul_f32_e32 v130, v45, v45
	v_mul_f32_e32 v131, v43, v43
	v_fmac_f32_e32 v128, v50, v50
	v_fmac_f32_e32 v129, v48, v48
	v_add_f32_e32 v124, v126, v127
	v_add_f32_e32 v102, v102, v123
	v_mul_f32_e32 v132, v41, v41
	v_mul_f32_e32 v133, v39, v39
	v_fmac_f32_e32 v130, v44, v44
	v_fmac_f32_e32 v131, v42, v42
	v_add_f32_e32 v125, v128, v129
	v_add_f32_e32 v102, v102, v124
	v_mul_f32_e32 v134, v37, v37
	v_mul_f32_e32 v135, v35, v35
	v_fmac_f32_e32 v132, v40, v40
	v_fmac_f32_e32 v133, v38, v38
	v_add_f32_e32 v126, v130, v131
	v_add_f32_e32 v102, v102, v125
	v_fmac_f32_e32 v134, v36, v36
	v_fmac_f32_e32 v135, v34, v34
	v_add_f32_e32 v127, v132, v133
	v_add_f32_e32 v102, v102, v126
	v_add_f32_e32 v128, v134, v135
	v_add_f32_e32 v102, v102, v127
	v_add_f32_e32 v102, v102, v128
	s_nop 1
	v_add_f32_dpp v102, v102, v102 row_shr:1 row_mask:0xf bank_mask:0xf bound_ctrl:1
	s_nop 1
	v_add_f32_dpp v102, v102, v102 row_shr:2 row_mask:0xf bank_mask:0xf bound_ctrl:1
	s_nop 1
	v_add_f32_dpp v102, v102, v102 row_shr:4 row_mask:0xf bank_mask:0xf bound_ctrl:1
	s_nop 1
	v_add_f32_dpp v102, v102, v102 row_shr:8 row_mask:0xf bank_mask:0xf bound_ctrl:1
	s_nop 1
	v_mov_b32_dpp v67, v102 row_bcast:15 row_mask:0xa bank_mask:0xf bound_ctrl:1
	v_add_f32_e32 v67, v102, v67
	s_nop 1
	v_mov_b32_dpp v158, v67 row_bcast:31 row_mask:0xc bank_mask:0xf bound_ctrl:1
	v_add_f32_e32 v67, v67, v158
	s_nop 0
	v_readlane_b32 s0, v67, 63
	s_nop 1
	v_fma_f32 v67, s0, v65, v64
	v_mul_f32_e32 v102, 0x4f800000, v67
	v_cmp_gt_f32_e32 vcc, s7, v67
	s_nop 1
	v_cndmask_b32_e32 v67, v67, v102, vcc
	v_sqrt_f32_e32 v102, v67
	s_nop 0
	v_add_u32_e32 v103, -1, v102
	v_add_u32_e32 v104, 1, v102
	v_fma_f32 v105, -v103, v102, v67
	v_fma_f32 v106, -v104, v102, v67
	v_cmp_ge_f32_e64 s[0:1], 0, v105
	s_nop 1
	v_cndmask_b32_e64 v102, v102, v103, s[0:1]
	v_cmp_lt_f32_e64 s[0:1], 0, v106
	s_nop 1
	v_cndmask_b32_e64 v102, v102, v104, s[0:1]
	v_mul_f32_e32 v103, 0x37800000, v102
	v_cndmask_b32_e32 v102, v102, v103, vcc
	v_cmp_class_f32_e32 vcc, v67, v66
	s_nop 1
	v_cndmask_b32_e32 v67, v102, v67, vcc
	v_div_scale_f32 v102, s[0:1], v67, v67, 1.0
	v_rcp_f32_e32 v104, v102
	v_div_scale_f32 v103, vcc, 1.0, v67, 1.0
	v_fma_f32 v105, -v102, v104, 1.0
	v_fmac_f32_e32 v104, v105, v104
	v_mul_f32_e32 v105, v103, v104
	v_fma_f32 v106, -v102, v105, v103
	v_fmac_f32_e32 v105, v106, v104
	v_fma_f32 v102, -v102, v105, v103
	v_div_fmas_f32 v102, v102, v104, v105
	v_div_fixup_f32 v102, v102, v67, 1.0
	v_pk_mul_f32 v[68:69], v[68:69], v[102:103] op_sel_hi:[1,0]
	v_pk_mul_f32 v[70:71], v[70:71], v[102:103] op_sel_hi:[1,0]
	v_pk_mul_f32 v[0:1], v[0:1], v[68:69]
	v_pk_mul_f32 v[2:3], v[2:3], v[70:71]
	global_store_dwordx4 v[46:47], v[0:3], off offset:-3072
	global_load_dwordx4 v[0:3], v[4:5], off offset:1024
	v_pk_mul_f32 v[68:69], v[76:77], v[102:103] op_sel_hi:[1,0]
	v_pk_mul_f32 v[70:71], v[72:73], v[102:103] op_sel_hi:[1,0]
	v_pk_mul_f32 v[60:61], v[60:61], v[102:103] op_sel_hi:[1,0]
	v_pk_mul_f32 v[62:63], v[62:63], v[102:103] op_sel_hi:[1,0]
	v_pk_mul_f32 v[56:57], v[56:57], v[102:103] op_sel_hi:[1,0]
	v_pk_mul_f32 v[58:59], v[58:59], v[102:103] op_sel_hi:[1,0]
	v_pk_mul_f32 v[42:43], v[42:43], v[102:103] op_sel_hi:[1,0]
	v_pk_mul_f32 v[44:45], v[44:45], v[102:103] op_sel_hi:[1,0]
	v_pk_mul_f32 v[38:39], v[38:39], v[102:103] op_sel_hi:[1,0]
	v_pk_mul_f32 v[40:41], v[40:41], v[102:103] op_sel_hi:[1,0]
	v_pk_mul_f32 v[34:35], v[34:35], v[102:103] op_sel_hi:[1,0]
	v_pk_mul_f32 v[36:37], v[36:37], v[102:103] op_sel_hi:[1,0]
	s_waitcnt vmcnt(0)
	v_pk_mul_f32 v[0:1], v[0:1], v[70:71]
	v_pk_mul_f32 v[2:3], v[2:3], v[68:69]
	global_store_dwordx4 v[46:47], v[0:3], off offset:-2048
	global_load_dwordx4 v[0:3], v[4:5], off offset:2048
	v_pk_mul_f32 v[68:69], v[78:79], v[102:103] op_sel_hi:[1,0]
	v_pk_mul_f32 v[70:71], v[80:81], v[102:103] op_sel_hi:[1,0]
	s_waitcnt vmcnt(0)
	v_pk_mul_f32 v[2:3], v[2:3], v[68:69]
	v_pk_mul_f32 v[0:1], v[0:1], v[70:71]
	global_store_dwordx4 v[46:47], v[0:3], off offset:-1024
	global_load_dwordx4 v[0:3], v[4:5], off offset:3072
	v_add_co_u32_e32 v46, vcc, s9, v30
	v_pk_mul_f32 v[68:69], v[82:83], v[102:103] op_sel_hi:[1,0]
	v_pk_mul_f32 v[70:71], v[84:85], v[102:103] op_sel_hi:[1,0]
	v_addc_co_u32_e32 v47, vcc, -1, v31, vcc
	s_waitcnt vmcnt(0)
	v_pk_mul_f32 v[0:1], v[0:1], v[70:71]
	v_pk_mul_f32 v[2:3], v[2:3], v[68:69]
	global_store_dwordx4 v[46:47], v[0:3], off offset:-4096
	global_load_dwordx4 v[0:3], v[6:7], off
	v_pk_mul_f32 v[68:69], v[86:87], v[102:103] op_sel_hi:[1,0]
	v_pk_mul_f32 v[70:71], v[94:95], v[102:103] op_sel_hi:[1,0]
	s_waitcnt vmcnt(0)
	v_pk_mul_f32 v[2:3], v[68:69], v[2:3]
	v_pk_mul_f32 v[0:1], v[70:71], v[0:1]
	global_store_dwordx4 v[46:47], v[0:3], off offset:-3072
	global_load_dwordx4 v[0:3], v[8:9], off
	v_pk_mul_f32 v[68:69], v[88:89], v[102:103] op_sel_hi:[1,0]
	v_pk_mul_f32 v[70:71], v[96:97], v[102:103] op_sel_hi:[1,0]
	s_waitcnt vmcnt(0)
	v_pk_mul_f32 v[2:3], v[68:69], v[2:3]
	v_pk_mul_f32 v[0:1], v[70:71], v[0:1]
	global_store_dwordx4 v[46:47], v[0:3], off offset:-2048
	global_load_dwordx4 v[0:3], v[10:11], off
	v_pk_mul_f32 v[68:69], v[90:91], v[102:103] op_sel_hi:[1,0]
	v_pk_mul_f32 v[70:71], v[98:99], v[102:103] op_sel_hi:[1,0]
	s_waitcnt vmcnt(0)
	v_pk_mul_f32 v[2:3], v[68:69], v[2:3]
	v_pk_mul_f32 v[0:1], v[70:71], v[0:1]
	global_store_dwordx4 v[46:47], v[0:3], off offset:-1024
	global_load_dwordx4 v[0:3], v[12:13], off
	v_pk_mul_f32 v[68:69], v[92:93], v[102:103] op_sel_hi:[1,0]
	v_pk_mul_f32 v[70:71], v[108:109], v[102:103] op_sel_hi:[1,0]
	s_waitcnt vmcnt(0)
	v_pk_mul_f32 v[2:3], v[68:69], v[2:3]
	v_pk_mul_f32 v[0:1], v[70:71], v[0:1]
	global_store_dwordx4 v[46:47], v[0:3], off
	global_load_dwordx4 v[0:3], v[14:15], off
	v_add_co_u32_e32 v46, vcc, s3, v30
	v_pk_mul_f32 v[68:69], v[74:75], v[102:103] op_sel_hi:[1,0]
	v_pk_mul_f32 v[70:71], v[100:101], v[102:103] op_sel_hi:[1,0]
	v_addc_co_u32_e32 v47, vcc, -1, v31, vcc
	s_waitcnt vmcnt(0)
	v_pk_mul_f32 v[0:1], v[70:71], v[0:1]
	v_pk_mul_f32 v[2:3], v[68:69], v[2:3]
	global_store_dwordx4 v[46:47], v[0:3], off offset:-3072
	global_load_dwordx4 v[0:3], v[16:17], off
	s_waitcnt vmcnt(0)
	v_pk_mul_f32 v[0:1], v[62:63], v[0:1]
	v_pk_mul_f32 v[2:3], v[60:61], v[2:3]
	global_store_dwordx4 v[46:47], v[0:3], off offset:-2048
	global_load_dwordx4 v[0:3], v[18:19], off
	s_waitcnt vmcnt(0)
	v_pk_mul_f32 v[0:1], v[58:59], v[0:1]
	v_pk_mul_f32 v[2:3], v[56:57], v[2:3]
	global_store_dwordx4 v[46:47], v[0:3], off offset:-1024
	global_load_dwordx4 v[0:3], v[20:21], off
	v_pk_mul_f32 v[46:47], v[52:53], v[102:103] op_sel_hi:[1,0]
	v_pk_mul_f32 v[52:53], v[54:55], v[102:103] op_sel_hi:[1,0]
	s_waitcnt vmcnt(0)
	v_pk_mul_f32 v[2:3], v[46:47], v[2:3]
	v_pk_mul_f32 v[0:1], v[52:53], v[0:1]
	global_store_dwordx4 v[30:31], v[0:3], off offset:-4096
	global_load_dwordx4 v[0:3], v[22:23], off
	v_pk_mul_f32 v[46:47], v[48:49], v[102:103] op_sel_hi:[1,0]
	v_pk_mul_f32 v[48:49], v[50:51], v[102:103] op_sel_hi:[1,0]
	s_waitcnt vmcnt(0)
	v_pk_mul_f32 v[2:3], v[46:47], v[2:3]
	v_pk_mul_f32 v[0:1], v[48:49], v[0:1]
	global_store_dwordx4 v[30:31], v[0:3], off offset:-3072
	global_load_dwordx4 v[0:3], v[24:25], off
	s_waitcnt vmcnt(0)
	v_pk_mul_f32 v[0:1], v[44:45], v[0:1]
	v_pk_mul_f32 v[2:3], v[42:43], v[2:3]
	global_store_dwordx4 v[30:31], v[0:3], off offset:-2048
	global_load_dwordx4 v[0:3], v[26:27], off
	s_waitcnt vmcnt(0)
	v_pk_mul_f32 v[0:1], v[40:41], v[0:1]
	v_pk_mul_f32 v[2:3], v[38:39], v[2:3]
	global_store_dwordx4 v[30:31], v[0:3], off offset:-1024
	global_load_dwordx4 v[0:3], v[28:29], off
	s_waitcnt vmcnt(0)
	v_pk_mul_f32 v[0:1], v[36:37], v[0:1]
	v_pk_mul_f32 v[2:3], v[34:35], v[2:3]
	global_store_dwordx4 v[30:31], v[0:3], off
	v_lshl_add_u64 v[30:31], v[30:31], 0, s[4:5]
	s_cbranch_scc1 .LBB0_836
